# e29 loop-edge: B-loop rescale test reads both alpha words up front, single combined branch (no second LDS round trip on the no-rescale path)
# speedup vs baseline: 1.0025x; 1.0025x over previous
; __device__ __forceinline__ int crow(int r, int hi) { return (r & 3) + 8 * (r >> 2) + 4 * hi; }
; __device__ __forceinline__ int crow(int r, int hi) { return (r & 3) + 8 * (r >> 2) + 4 * hi; }
; #define DMA_K(j_, b_) do { const char* kb_ = (const char*)Kh + (size_t)(j_) * (64 * LD * 2); _Pragma("unroll") for (int i = 0; i < 4; ++i) \
;     __builtin_amdgcn_global_load_lds((const unsigned*)(kb_ + kgo[i]), (LAS unsigned*)(K_las + (b_) * 16384 + (4 * a + i) * 1024), 16, 0, 0); } while (0)
; #define DMA_V(j_, b_) do { const char* vb_ = (const char*)Vh + (size_t)(j_) * (64 * LD * 2); _Pragma("unroll") for (int hf = 0; hf < 2; ++hf) _Pragma("unroll") for (int i = 0; i < 4; ++i) \
;     __builtin_amdgcn_global_load_lds((const unsigned*)(vb_ + hf * 256 + vgo[i]), (LAS unsigned*)(V_las + (b_) * 32768 + hf * 16384 + (4 * a + i) * 1024), 16, 0, 0); } while (0)
; __device__ __forceinline__ void attn_unit2(const bf16* __restrict__ Qb, const bf16* __restrict__ Kh, const bf16* __restrict__ Vh, bf16* __restrict__ Ob,
;                                            int NT, int lim, int qrow0, const float* lut, char* lds, float* scr) {
;     ...
;       if (j + 1 < NT) DMA_K(j + 1, (j + 1) & 1);
;       if (j < NT) DMA_V(j, j & 1);
;       if (j >= 1) {
;         const float* al = al0 + ((j - 1) & 1) * 128;
;         if (__any(al[r32] < 1.f) || __any(al[32 + r32] < 1.f)) {
; #pragma unroll
;           for (int rb = 0; rb < 2; ++rb)
; #pragma unroll
;             for (int d = 0; d < 4; ++d)
; #pragma unroll
;               for (int r = 0; r < 16; ++r) o[rb][d][r] *= al[rb * 32 + crow(r, hi)]; }
.LBB0_433:
	s_and_b32 s14, s10, 1
	s_lshl_b32 s15, s14, 9
	s_add_i32 s15, s4, s15
	v_lshl_add_u32 v177, v172, 2, s15
	ds_read_b32 v200, v177
	ds_read_b32 v201, v177 offset:128
	s_and_b32 s23, s9, 0x8000
	s_add_i32 s23, s6, s23
	v_lshl_add_u64 v[156:157], v[138:139], 0, s[36:37]
	s_add_i32 m0, s23, 0x8000
	v_lshl_add_u64 v[158:159], v[156:157], 0, s[54:55]
	global_load_lds_dwordx4 v[158:159], off
	v_lshl_add_u64 v[158:159], v[142:143], 0, s[36:37]
	v_lshl_add_u64 v[164:165], v[158:159], 0, s[54:55]
	s_add_i32 m0, s23, 0x8400
	v_lshl_add_u64 v[156:157], v[156:157], 0, s[68:69]
	global_load_lds_dwordx4 v[164:165], off
	v_lshl_add_u64 v[164:165], v[144:145], 0, s[36:37]
	v_lshl_add_u64 v[178:179], v[164:165], 0, s[54:55]
	s_add_i32 m0, s23, 0x8800
	s_nop 0
	global_load_lds_dwordx4 v[178:179], off
	v_lshl_add_u64 v[178:179], v[146:147], 0, s[36:37]
	v_lshl_add_u64 v[180:181], v[178:179], 0, s[54:55]
	s_add_i32 m0, s23, 0x8c00
	s_nop 0
	global_load_lds_dwordx4 v[180:181], off
	v_lshl_add_u64 v[158:159], v[158:159], 0, s[68:69]
	v_lshl_add_u64 v[164:165], v[164:165], 0, s[68:69]
	v_lshl_add_u64 v[252:253], v[178:179], 0, s[68:69]
	s_waitcnt lgkmcnt(0)
	v_cmp_gt_f32_e32 vcc, 1.0, v200
	v_cmp_gt_f32_e64 s[46:47], 1.0, v201
	s_or_b64 vcc, vcc, s[46:47]
	s_cbranch_vccz .LBB0_436
.LBB0_435:
	v_add_u32_e32 v201, s15, v140
	ds_read_b128 v[178:181], v201
	s_nop 0
	ds_read_b128 v[182:185], v201 offset:32
	ds_read_b128 v[186:189], v201 offset:64
	ds_read_b128 v[190:193], v201 offset:96
	s_waitcnt lgkmcnt(0)
	v_pk_mul_f32 v[118:119], v[118:119], v[180:181]
	v_pk_mul_f32 v[120:121], v[120:121], v[182:183]
	v_pk_mul_f32 v[124:125], v[124:125], v[186:187]
	v_pk_mul_f32 v[128:129], v[128:129], v[190:191]
	s_nop 0
	v_pk_mul_f32 v[130:131], v[130:131], v[192:193]
	v_pk_mul_f32 v[126:127], v[126:127], v[188:189]
	v_pk_mul_f32 v[122:123], v[122:123], v[184:185]
	v_pk_mul_f32 v[116:117], v[116:117], v[178:179]
	v_pk_mul_f32 v[112:113], v[112:113], v[190:191]
	v_pk_mul_f32 v[108:109], v[108:109], v[186:187]
	v_pk_mul_f32 v[104:105], v[104:105], v[182:183]
	v_pk_mul_f32 v[114:115], v[114:115], v[192:193]
	v_pk_mul_f32 v[110:111], v[110:111], v[188:189]
	v_pk_mul_f32 v[106:107], v[106:107], v[184:185]
	v_pk_mul_f32 v[102:103], v[102:103], v[180:181]
	v_pk_mul_f32 v[100:101], v[100:101], v[178:179]
	v_pk_mul_f32 v[96:97], v[96:97], v[190:191]
	v_pk_mul_f32 v[92:93], v[92:93], v[186:187]
	v_pk_mul_f32 v[88:89], v[88:89], v[182:183]
	v_pk_mul_f32 v[98:99], v[98:99], v[192:193]
	v_pk_mul_f32 v[94:95], v[94:95], v[188:189]
	v_pk_mul_f32 v[90:91], v[90:91], v[184:185]
	v_pk_mul_f32 v[86:87], v[86:87], v[180:181]
	v_pk_mul_f32 v[84:85], v[84:85], v[178:179]
	v_pk_mul_f32 v[80:81], v[80:81], v[190:191]
	v_pk_mul_f32 v[76:77], v[76:77], v[186:187]
	v_pk_mul_f32 v[72:73], v[72:73], v[182:183]
	v_pk_mul_f32 v[82:83], v[82:83], v[192:193]
	v_pk_mul_f32 v[78:79], v[78:79], v[188:189]
	v_pk_mul_f32 v[74:75], v[74:75], v[184:185]
	v_pk_mul_f32 v[70:71], v[70:71], v[180:181]
	v_pk_mul_f32 v[68:69], v[68:69], v[178:179]
	ds_read_b128 v[178:181], v201 offset:128
	ds_read_b128 v[182:185], v201 offset:160
	ds_read_b128 v[186:189], v201 offset:192
	ds_read_b128 v[190:193], v201 offset:224
	s_waitcnt lgkmcnt(0)
	v_pk_mul_f32 v[54:55], v[54:55], v[180:181]
	v_pk_mul_f32 v[56:57], v[56:57], v[182:183]
	v_pk_mul_f32 v[60:61], v[60:61], v[186:187]
	v_pk_mul_f32 v[64:65], v[64:65], v[190:191]
	v_pk_mul_f32 v[66:67], v[66:67], v[192:193]
	v_pk_mul_f32 v[62:63], v[62:63], v[188:189]
	v_pk_mul_f32 v[58:59], v[58:59], v[184:185]
	s_nop 0
	v_pk_mul_f32 v[52:53], v[52:53], v[178:179]
	v_pk_mul_f32 v[48:49], v[48:49], v[190:191]
	v_pk_mul_f32 v[44:45], v[44:45], v[186:187]
	v_pk_mul_f32 v[40:41], v[40:41], v[182:183]
	v_pk_mul_f32 v[50:51], v[50:51], v[192:193]
	v_pk_mul_f32 v[46:47], v[46:47], v[188:189]
	v_pk_mul_f32 v[42:43], v[42:43], v[184:185]
	v_pk_mul_f32 v[38:39], v[38:39], v[180:181]
	v_pk_mul_f32 v[36:37], v[36:37], v[178:179]
	v_pk_mul_f32 v[32:33], v[32:33], v[190:191]
	v_pk_mul_f32 v[28:29], v[28:29], v[186:187]
	v_pk_mul_f32 v[24:25], v[24:25], v[182:183]
	v_pk_mul_f32 v[34:35], v[34:35], v[192:193]
	v_pk_mul_f32 v[30:31], v[30:31], v[188:189]
	v_pk_mul_f32 v[26:27], v[26:27], v[184:185]
	v_pk_mul_f32 v[22:23], v[22:23], v[180:181]
	v_pk_mul_f32 v[20:21], v[20:21], v[178:179]
	v_pk_mul_f32 v[16:17], v[16:17], v[190:191]
	v_pk_mul_f32 v[12:13], v[12:13], v[186:187]
	v_pk_mul_f32 v[8:9], v[8:9], v[182:183]
	v_pk_mul_f32 v[18:19], v[18:19], v[192:193]
	v_pk_mul_f32 v[14:15], v[14:15], v[188:189]
	v_pk_mul_f32 v[10:11], v[10:11], v[184:185]
	v_pk_mul_f32 v[6:7], v[6:7], v[180:181]
	v_pk_mul_f32 v[4:5], v[4:5], v[178:179]
; #define SBAR() __builtin_amdgcn_sched_barrier(0)
; #define VRD(D0, L) const s16x4 L##0 = tr_read<v_rd_off(D0, 0, 0)>(vb), L##1 = tr_read<v_rd_off(D0, 0, 1)>(vb), L##2 = tr_read<v_rd_off(D0, 1, 0)>(vb), L##3 = tr_read<v_rd_off(D0, 1, 1)>(vb), \
;                          L##4 = tr_read<v_rd_off(D0, 2, 0)>(vb), L##5 = tr_read<v_rd_off(D0, 2, 1)>(vb), L##6 = tr_read<v_rd_off(D0, 3, 0)>(vb), L##7 = tr_read<v_rd_off(D0, 3, 1)>(vb)
; __device__ __forceinline__ void pv_four(f32x16 (&o)[2][4], int vb, bf16x8 pa0, bf16x8 pa1, bf16x8 pa2, bf16x8 pa3, bf16x8 pb0, bf16x8 pb1, bf16x8 pb2, bf16x8 pb3) {
;     ...
;   VRD(0, x); SBAR();
;   VRD(1, y); asm volatile("s_waitcnt lgkmcnt(8)" ::: "memory"); SBAR(); MMA(0, x); SBAR();
;   VRD(2, z); asm volatile("s_waitcnt lgkmcnt(8)" ::: "memory"); SBAR(); MMA(1, y); SBAR();
;   VRD(3, w); asm volatile("s_waitcnt lgkmcnt(8)" ::: "memory"); SBAR(); MMA(2, z); SBAR();
;   asm volatile("s_waitcnt lgkmcnt(0)" ::: "memory"); SBAR(); MMA(3, w);
;     ...
; }
; __device__ __forceinline__ void attn_unit2(const bf16* __restrict__ Qb, const bf16* __restrict__ Kh, const bf16* __restrict__ Vh, bf16* __restrict__ Ob,
;                                            int NT, int lim, int qrow0, const float* lut, char* lds, float* scr) {
;     ...
;         const char* ps = P0 + ((j - 1) & 1) * 16384 + lane * 16;
;         const bf16x8 pa0 = *(const bf16x8*)(ps), pa1 = *(const bf16x8*)(ps + 1024), pa2 = *(const bf16x8*)(ps + 2048), pa3 = *(const bf16x8*)(ps + 3072);
;         const bf16x8 pb0 = *(const bf16x8*)(ps + 4096), pb1 = *(const bf16x8*)(ps + 4096 + 1024), pb2 = *(const bf16x8*)(ps + 4096 + 2048), pb3 = *(const bf16x8*)(ps + 4096 + 3072);
;         const int vb = vrb + ((j - 1) & 1) * 32768 + ch * 16384;
;         pv_four(o, vb, pa0, pa1, pa2, pa3, pb0, pb1, pb2, pb3);
;       }
;       asm volatile("s_waitcnt vmcnt(0)" ::: "memory");
;       __syncthreads();
.LBB0_436:
	v_lshl_add_u32 v201, s14, 14, v175
	ds_read_b128 v[178:181], v201
	ds_read_b128 v[182:185], v201 offset:1024
	ds_read_b128 v[186:189], v201 offset:2048
	ds_read_b128 v[190:193], v201 offset:3072
	ds_read_b128 v[194:197], v201 offset:4096
	ds_read_b128 v[208:211], v201 offset:5120
	ds_read_b128 v[212:215], v201 offset:6144
	ds_read_b128 v[216:219], v201 offset:7168
	v_lshl_add_u32 v207, s14, 15, v176
	ds_read_b64_tr_b16 v[220:221], v207 offset:0
	ds_read_b64_tr_b16 v[222:223], v207 offset:0x800
	ds_read_b64_tr_b16 v[224:225], v207 offset:0x1000
	ds_read_b64_tr_b16 v[226:227], v207 offset:0x1800
	ds_read_b64_tr_b16 v[228:229], v207 offset:0x2000
	ds_read_b64_tr_b16 v[230:231], v207 offset:0x2800
	ds_read_b64_tr_b16 v[232:233], v207 offset:0x3000
	ds_read_b64_tr_b16 v[234:235], v207 offset:0x3800
	ds_read_b64_tr_b16 v[236:237], v207 offset:0x200
	ds_read_b64_tr_b16 v[238:239], v207 offset:0xa00
	ds_read_b64_tr_b16 v[240:241], v207 offset:0x1200
	ds_read_b64_tr_b16 v[242:243], v207 offset:0x1a00
	ds_read_b64_tr_b16 v[244:245], v207 offset:0x2200
	ds_read_b64_tr_b16 v[246:247], v207 offset:0x2a00
	ds_read_b64_tr_b16 v[248:249], v207 offset:0x3200
	ds_read_b64_tr_b16 v[250:251], v207 offset:0x3a00
	s_add_i32 m0, s23, 0xc000
	s_nop 0
	global_load_lds_dwordx4 v[156:157], off
	s_add_i32 m0, s23, 0xc400
	s_nop 0
	global_load_lds_dwordx4 v[158:159], off
	s_add_i32 m0, s23, 0xc800
	s_nop 0
	global_load_lds_dwordx4 v[164:165], off
	s_add_i32 m0, s23, 0xcc00
	s_nop 0
	global_load_lds_dwordx4 v[252:253], off
	s_waitcnt lgkmcnt(8)
	s_waitcnt lgkmcnt(0)
	v_mfma_f32_32x32x16_bf16 v[116:131], v[178:181], v[220:223], v[116:131]
	v_mfma_f32_32x32x16_bf16 v[52:67], v[194:197], v[220:223], v[52:67]
	v_mfma_f32_32x32x16_bf16 v[116:131], v[182:185], v[224:227], v[116:131]
	v_mfma_f32_32x32x16_bf16 v[52:67], v[208:211], v[224:227], v[52:67]
	v_mfma_f32_32x32x16_bf16 v[116:131], v[186:189], v[228:231], v[116:131]
	v_mfma_f32_32x32x16_bf16 v[52:67], v[212:215], v[228:231], v[52:67]
	v_mfma_f32_32x32x16_bf16 v[116:131], v[190:193], v[232:235], v[116:131]
	v_mfma_f32_32x32x16_bf16 v[52:67], v[216:219], v[232:235], v[52:67]
	ds_read_b64_tr_b16 v[220:221], v207 offset:0x400
	ds_read_b64_tr_b16 v[222:223], v207 offset:0xc00
	ds_read_b64_tr_b16 v[224:225], v207 offset:0x1400
	ds_read_b64_tr_b16 v[226:227], v207 offset:0x1c00
	ds_read_b64_tr_b16 v[228:229], v207 offset:0x2400
	ds_read_b64_tr_b16 v[230:231], v207 offset:0x2c00
	ds_read_b64_tr_b16 v[232:233], v207 offset:0x3400
	ds_read_b64_tr_b16 v[234:235], v207 offset:0x3c00
	s_waitcnt lgkmcnt(8)
	v_mfma_f32_32x32x16_bf16 v[100:115], v[178:181], v[236:239], v[100:115]
	s_nop 0
	v_mfma_f32_32x32x16_bf16 v[36:51], v[194:197], v[236:239], v[36:51]
	v_mfma_f32_32x32x16_bf16 v[100:115], v[182:185], v[240:243], v[100:115]
	v_mfma_f32_32x32x16_bf16 v[36:51], v[208:211], v[240:243], v[36:51]
	v_mfma_f32_32x32x16_bf16 v[100:115], v[186:189], v[244:247], v[100:115]
	v_mfma_f32_32x32x16_bf16 v[36:51], v[212:215], v[244:247], v[36:51]
	v_mfma_f32_32x32x16_bf16 v[100:115], v[190:193], v[248:251], v[100:115]
	v_mfma_f32_32x32x16_bf16 v[36:51], v[216:219], v[248:251], v[36:51]
	ds_read_b64_tr_b16 v[236:237], v207 offset:0x600
	ds_read_b64_tr_b16 v[238:239], v207 offset:0xe00
	ds_read_b64_tr_b16 v[240:241], v207 offset:0x1600
	ds_read_b64_tr_b16 v[242:243], v207 offset:0x1e00
	ds_read_b64_tr_b16 v[244:245], v207 offset:0x2600
	ds_read_b64_tr_b16 v[246:247], v207 offset:0x2e00
	ds_read_b64_tr_b16 v[248:249], v207 offset:0x3600
	ds_read_b64_tr_b16 v[250:251], v207 offset:0x3e00
	s_waitcnt lgkmcnt(8)
	s_nop 0
	v_mfma_f32_32x32x16_bf16 v[84:99], v[178:181], v[220:223], v[84:99]
	v_mfma_f32_32x32x16_bf16 v[20:35], v[194:197], v[220:223], v[20:35]
	v_mfma_f32_32x32x16_bf16 v[84:99], v[182:185], v[224:227], v[84:99]
	v_mfma_f32_32x32x16_bf16 v[20:35], v[208:211], v[224:227], v[20:35]
	v_mfma_f32_32x32x16_bf16 v[84:99], v[186:189], v[228:231], v[84:99]
	v_mfma_f32_32x32x16_bf16 v[20:35], v[212:215], v[228:231], v[20:35]
	v_mfma_f32_32x32x16_bf16 v[84:99], v[190:193], v[232:235], v[84:99]
	v_mfma_f32_32x32x16_bf16 v[20:35], v[216:219], v[232:235], v[20:35]
	s_waitcnt lgkmcnt(0)
	v_mfma_f32_32x32x16_bf16 v[68:83], v[178:181], v[236:239], v[68:83]
	s_add_i32 s9, s9, 0x8000
	s_waitcnt vmcnt(0)
	s_add_u32 s36, s36, 0x40000
	s_addc_u32 s37, s37, 0
	s_add_i32 s14, s10, 1
	s_addk_i32 s7, 0x4000
	s_cmp_eq_u32 s8, s36
	v_mfma_f32_32x32x16_bf16 v[4:19], v[194:197], v[236:239], v[4:19]
	s_waitcnt vmcnt(0)
	s_barrier
	v_mfma_f32_32x32x16_bf16 v[68:83], v[182:185], v[240:243], v[68:83]
	v_mfma_f32_32x32x16_bf16 v[4:19], v[208:211], v[240:243], v[4:19]
	v_mfma_f32_32x32x16_bf16 v[68:83], v[186:189], v[244:247], v[68:83]
	v_mfma_f32_32x32x16_bf16 v[4:19], v[212:215], v[244:247], v[4:19]
	v_mfma_f32_32x32x16_bf16 v[68:83], v[190:193], v[248:251], v[68:83]
	v_mfma_f32_32x32x16_bf16 v[4:19], v[216:219], v[248:251], v[4:19]
	s_cbranch_scc1 .LBB0_439
	s_mov_b32 s10, s14
	s_cmp_lt_u32 s10, s5
	s_cselect_b64 s[38:39], -1, 0
	s_cmp_ge_u32 s10, s5
	s_cbranch_scc0 .LBB0_432
	s_branch .LBB0_433
	s_nop 0
